# P4 stage S3: eight per-token bonus sums gathered by writelane and stored with one 8-lane store instead of eight exec-masked blocks
# baseline (speedup 1.0000x reference)
; __device__ __forceinline__ bf16_t f2bf(float f) { return (bf16_t)(pk2(f, 0.f) & 0xffffu); }
; __device__ __forceinline__ float sigmoidf_(float x) { return frcp(1.0f + __expf(-x)); }
; __device__ __forceinline__ void rwkv_phase_a(const Ctx& C) {
;     ...
; #pragma unroll
;             for (int i = 0; i < 2; ++i) {
;                 const int ch = nc0 + 16 * i; const float w0c = w0[h * 64 + ch], a0c = a0[h * 64 + ch];
; #pragma unroll
;                 for (int j = 0; j < 4; ++j) {
;                     const int t = mt * 16 + 4 * q + j;
;                     FM(0)[t * MS + ch] = -0.60653065971f * sigmoidf_(w0c + aw[i][j]);
;                     FM(1)[t * MS + ch] = sigmoidf_(a0c + aa[i][j]);
;                     Gg[(size_t)(tok0 + t) * GWD_ + h * 64 + ch] = f2bf(ag[i][j]);
;                 }
;             }
;         }
;         __syncthreads();
.LBB0_721:
	v_add_u32_e32 v106, s92, v138
	v_ashrrev_i32_e32 v107, 31, v106
	s_add_u32 s22, s26, s18
	v_add_u32_e32 v108, s93, v138
	v_lshlrev_b64 v[100:101], 10, v[106:107]
	s_addc_u32 s23, s27, s19
	v_ashrrev_i32_e32 v109, 31, v108
	v_lshl_or_b32 v100, v122, 1, v100
	v_add_lshl_u32 v118, s56, v209, 1
	v_add_u32_e32 v110, s94, v138
	v_lshlrev_b64 v[98:99], 10, v[108:109]
	v_lshl_add_u64 v[100:101], s[22:23], 0, v[100:101]
	v_ashrrev_i32_e32 v111, 31, v110
	v_or_b32_e32 v98, v98, v118
	v_add_co_u32_e32 v100, vcc, s6, v100
	v_lshlrev_b64 v[106:107], 10, v[110:111]
	v_lshl_add_u64 v[98:99], s[22:23], 0, v[98:99]
	v_addc_co_u32_e32 v101, vcc, 0, v101, vcc
	v_or_b32_e32 v106, v106, v118
	v_add_co_u32_e32 v98, vcc, s6, v98
	v_lshl_add_u64 v[106:107], s[22:23], 0, v[106:107]
	s_nop 0
	v_addc_co_u32_e32 v99, vcc, 0, v99, vcc
	v_cvt_pk_bf16_f32 v116, v182, s0
	v_cvt_pk_bf16_f32 v117, v183, s0
	v_add_co_u32_e32 v106, vcc, s6, v106
	v_cvt_pk_bf16_f32 v119, v184, s0
	s_nop 0
	v_addc_co_u32_e32 v107, vcc, 0, v107, vcc
	global_store_short v[100:101], v116, off
	global_store_short v[98:99], v117, off
	global_store_short v[106:107], v119, off
	v_lshl_add_u32 v112, v112, 2, 0
	v_cvt_pk_bf16_f32 v120, v185, s0
	v_readlane_b32 s44, v254, 10
	v_readlane_b32 s45, v254, 11
	v_readlane_b32 s48, v254, 14
	v_readlane_b32 s49, v254, 15
	v_readlane_b32 s50, v254, 16
	v_readlane_b32 s51, v254, 17
	s_mov_b64 s[52:53], s[40:41]
	v_readlane_b32 s40, v254, 42
	v_readlane_b32 s41, v254, 43
	s_movk_i32 s14, 0x220
	v_readlane_b32 s46, v254, 48
	v_readlane_b32 s47, v254, 49
	v_readlane_b32 s48, v254, 50
	v_readlane_b32 s44, v254, 46
	v_readlane_b32 s45, v254, 47
	v_readlane_b32 s42, v254, 44
	v_readlane_b32 s43, v254, 45
	v_readlane_b32 s49, v254, 51
	v_readlane_b32 s50, v254, 52
	v_readlane_b32 s51, v254, 53
	v_readlane_b32 s52, v254, 54
	v_readlane_b32 s53, v254, 55
	v_readlane_b32 s54, v254, 56
	v_readlane_b32 s55, v254, 57
	s_waitcnt vmcnt(52)
	v_add_f32_e32 v108, v150, v114
	v_add_f32_e32 v110, v151, v114
	s_waitcnt vmcnt(51)
	v_add_f32_e32 v109, v154, v115
	v_mul_f32_e32 v108, 0xbfb8aa3b, v108
	v_mul_f32_e32 v109, 0xbfb8aa3b, v109
	v_mul_f32_e32 v110, 0xbfb8aa3b, v110
	v_exp_f32_e32 v108, v108
	v_exp_f32_e32 v109, v109
	v_exp_f32_e32 v110, v110
	v_add_f32_e32 v111, v155, v115
	v_add_f32_e32 v116, v152, v114
	v_add_f32_e32 v117, v156, v115
	v_mul_f32_e32 v111, 0xbfb8aa3b, v111
	v_mul_f32_e32 v116, 0xbfb8aa3b, v116
	v_mul_f32_e32 v117, 0xbfb8aa3b, v117
	s_waitcnt vmcnt(49)
	v_add_f32_e32 v102, v102, v113
	v_exp_f32_e32 v111, v111
	v_exp_f32_e32 v116, v116
	v_exp_f32_e32 v117, v117
	v_add_f32_e32 v108, 1.0, v108
	v_mul_f32_e32 v102, 0xbfb8aa3b, v102
	v_add_f32_e32 v109, 1.0, v109
	v_add_f32_e32 v110, 1.0, v110
	v_rcp_f32_e32 v108, v108
	v_exp_f32_e32 v102, v102
	v_rcp_f32_e32 v119, v109
	v_rcp_f32_e32 v109, v110
	v_add_f32_e32 v111, 1.0, v111
	v_add_f32_e32 v116, 1.0, v116
	v_add_f32_e32 v117, 1.0, v117
	v_rcp_f32_e32 v110, v111
	v_rcp_f32_e32 v111, v116
	v_rcp_f32_e32 v116, v117
	v_mul_f32_e32 v117, 0xbf1b4598, v108
	v_add_u32_e32 v108, s95, v138
	v_add_f32_e32 v102, 1.0, v102
	v_mul_f32_e32 v124, 0xbf1b4598, v109
	v_ashrrev_i32_e32 v109, 31, v108
	v_rcp_f32_e32 v102, v102
	v_lshlrev_b64 v[108:109], 10, v[108:109]
	v_or_b32_e32 v108, v108, v118
	v_add_f32_e32 v118, v134, v121
	v_mul_f32_e32 v118, 0xbfb8aa3b, v118
	v_add_f32_e32 v103, v103, v113
	v_exp_f32_e32 v118, v118
	v_mul_f32_e32 v102, 0xbf1b4598, v102
	v_mul_f32_e32 v103, 0xbfb8aa3b, v103
	ds_write2_b32 v112, v117, v102 offset1:16
	v_exp_f32_e32 v103, v103
	v_add_f32_e32 v117, v135, v121
	v_mul_f32_e32 v117, 0xbfb8aa3b, v117
	v_exp_f32_e32 v117, v117
	v_add_f32_e32 v118, 1.0, v118
	v_rcp_f32_e32 v118, v118
	v_add_f32_e32 v103, 1.0, v103
	v_rcp_f32_e32 v103, v103
	v_lshl_add_u64 v[108:109], s[22:23], 0, v[108:109]
	v_add_f32_e32 v117, 1.0, v117
	v_add_co_u32_e32 v108, vcc, s6, v108
	v_add_u32_e32 v102, 0x4400, v112
	v_rcp_f32_e32 v117, v117
	v_addc_co_u32_e32 v109, vcc, 0, v109, vcc
	ds_write2_b32 v102, v119, v118 offset1:16
	v_cvt_pk_bf16_f32 v118, v146, s0
	global_store_short v[108:109], v120, off
	global_store_short v[100:101], v118, off offset:32
	v_mul_f32_e32 v100, 0xbf1b4598, v103
	ds_write2_b32 v112, v124, v100 offset0:68 offset1:84
	ds_write2_b32 v102, v110, v117 offset0:68 offset1:84
	v_add_f32_e32 v100, v104, v113
	v_mul_f32_e32 v100, 0xbfb8aa3b, v100
	v_exp_f32_e32 v100, v100
	v_add_f32_e32 v101, v136, v121
	v_mul_f32_e32 v101, 0xbfb8aa3b, v101
	v_exp_f32_e32 v101, v101
	v_add_f32_e32 v100, 1.0, v100
	v_rcp_f32_e32 v100, v100
	v_cvt_pk_bf16_f32 v103, v147, s0
	v_add_f32_e32 v101, 1.0, v101
	v_rcp_f32_e32 v101, v101
	v_mul_f32_e32 v111, 0xbf1b4598, v111
	global_store_short v[98:99], v103, off offset:32
	v_mul_f32_e32 v98, 0xbf1b4598, v100
	v_add_f32_e32 v114, v153, v114
	ds_write2_b32 v112, v111, v98 offset0:136 offset1:152
	ds_write2_b32 v102, v116, v101 offset0:136 offset1:152
	v_add_f32_e32 v98, v105, v113
	v_mul_f32_e32 v114, 0xbfb8aa3b, v114
	v_mul_f32_e32 v98, 0xbfb8aa3b, v98
	v_add_f32_e32 v115, v157, v115
	v_exp_f32_e32 v114, v114
	v_exp_f32_e32 v98, v98
	v_add_f32_e32 v99, v137, v121
	v_mul_f32_e32 v115, 0xbfb8aa3b, v115
	v_mul_f32_e32 v99, 0xbfb8aa3b, v99
	v_exp_f32_e32 v115, v115
	v_exp_f32_e32 v99, v99
	v_add_f32_e32 v114, 1.0, v114
	v_add_f32_e32 v98, 1.0, v98
	v_rcp_f32_e32 v114, v114
	v_rcp_f32_e32 v98, v98
	v_add_f32_e32 v115, 1.0, v115
	v_add_f32_e32 v99, 1.0, v99
	v_rcp_f32_e32 v115, v115
	v_rcp_f32_e32 v99, v99
	v_mul_f32_e32 v114, 0xbf1b4598, v114
	v_cvt_pk_bf16_f32 v100, v148, s0
	v_mul_f32_e32 v98, 0xbf1b4598, v98
	global_store_short v[106:107], v100, off offset:32
	ds_write2_b32 v112, v114, v98 offset0:204 offset1:220
	ds_write2_b32 v102, v115, v99 offset0:204 offset1:220
	v_cvt_pk_bf16_f32 v98, v149, s0
	global_store_short v[108:109], v98, off offset:32
	v_lshlrev_b64 v[98:99], 2, v[188:189]
	v_lshl_add_u64 v[100:101], s[64:65], 0, v[98:99]
	s_waitcnt lgkmcnt(0)
	s_barrier
; __device__ __forceinline__ float wave_sum(float v) {
;     v += dpp_f(v, 0); v += dpp_f(v, 1); v += dpp_f(v, 2); v += dpp_f(v, 3);
;     const int vi = __float_as_int(v);
;     const float s0 = __int_as_float(__builtin_amdgcn_readlane(vi, 0)), s1 = __int_as_float(__builtin_amdgcn_readlane(vi, 16)), s2 = __int_as_float(__builtin_amdgcn_readlane(vi, 32)), s3 = __int_as_float(__builtin_amdgcn_readlane(vi, 48));
;     return (s0 + s1) + (s2 + s3);
; __device__ __forceinline__ void rwkv_phase_a(const Ctx& C) {
;     ...
;             for (int u = 0; u < 8; ++u) {
;                 const int t = tg8 * 8 + u;
;                 ld[u] = FM(0)[t * MS + ci]; av[u] = FM(1)[t * MS + ci];
;                 const float kr = kx[u] * kkc; const float n2 = wave_sum(kr * kr);
;                 kkv[u] = kr * __builtin_amdgcn_rsqf(fmaxf(n2, 1e-24f));
;                 k2[u] = kx[u] * (1.0f + (av[u] - 1.0f) * kac);
;                 const float bs = wave_sum(rr[u] * k2[u] * rkc);
;                 if (lane == 0) bon[(size_t)(tok0 + t) * 8 + h] = bs;
;                 run += ld[u]; cl[u] = run;
;             }
	s_waitcnt vmcnt(51)
	v_lshl_add_u64 v[100:101], s[66:67], 0, v[98:99]
	v_mov_b32_e32 v125, v126
	v_lshl_add_u64 v[98:99], s[40:41], 0, v[98:99]
	v_mov_b32_e32 v117, v127
	v_mov_b32_e32 v124, v128
	v_cmp_lt_i32_e32 vcc, 0, v230
	v_lshlrev_b32_e32 v98, 16, v229
	v_and_b32_e32 v99, 0xffff0000, v229
	v_cndmask_b32_e64 v126, 0, 1.0, vcc
	v_fma_f32 v98, v126, v98, -v99
	v_fma_f32 v137, v223, v98, v99
	v_and_b32_e32 v98, 0xffff0000, v219
	v_lshlrev_b32_e32 v102, 16, v228
	v_fma_f32 v98, v126, v98, -v102
	v_fma_f32 v98, v222, v98, v102
	v_mad_u64_u32 v[100:101], s[14:15], v216, s14, v[192:193]
	v_lshl_add_u32 v100, v100, 2, 0
	ds_read2st64_b32 v[100:101], v100 offset1:68
	v_cmp_eq_u32_e32 vcc, 0, v192
	s_nop 0
	v_mul_f32_e32 v127, v98, v125
	v_mul_f32_e32 v103, v127, v127
	s_nop 1
	v_mov_b32_dpp v103, v103 quad_perm:[1,0,3,2] row_mask:0xf bank_mask:0xf
	v_fmac_f32_e32 v103, v127, v127
	s_nop 1
	v_add_f32_dpp v103, v103, v103 quad_perm:[2,3,0,1] row_mask:0xf bank_mask:0xf
	s_nop 1
	v_add_f32_dpp v103, v103, v103 row_half_mirror row_mask:0xf bank_mask:0xf
	s_nop 1
	v_add_f32_dpp v103, v103, v103 row_mirror row_mask:0xf bank_mask:0xf
	s_nop 0
	v_readlane_b32 s21, v103, 0
	v_readlane_b32 s47, v103, 16
	v_readlane_b32 s46, v103, 32
	v_readlane_b32 s48, v103, 48
	s_waitcnt lgkmcnt(0)
	v_add_f32_e32 v103, -1.0, v101
	s_nop 0
	v_fma_f32 v103, v117, v103, 1.0
	v_mul_f32_e32 v98, v98, v103
	v_mul_f32_e32 v103, v137, v98
	s_nop 0
	v_mul_f32_e32 v104, v124, v103
	s_nop 1
	v_mov_b32_dpp v104, v104 quad_perm:[1,0,3,2] row_mask:0xf bank_mask:0xf
	v_fmac_f32_e32 v104, v124, v103
	s_nop 1
	v_add_f32_dpp v103, v104, v104 quad_perm:[2,3,0,1] row_mask:0xf bank_mask:0xf
	s_nop 1
	v_add_f32_dpp v103, v103, v103 row_half_mirror row_mask:0xf bank_mask:0xf
	s_nop 1
	v_add_f32_dpp v103, v103, v103 row_mirror row_mask:0xf bank_mask:0xf
	s_nop 1
	v_add_f32_dpp v103, v103, v103 row_bcast:15 row_mask:0xa bank_mask:0xf
	s_nop 1
	v_add_f32_dpp v103, v103, v103 row_bcast:31 row_mask:0xc bank_mask:0xf
	s_nop 0
	v_readlane_b32 s44, v103, 63
	s_nop 1
	v_writelane_b32 v200, s44, 0
	v_lshlrev_b32_e32 v103, 16, v227
	v_sub_f32_e32 v99, v99, v103
	v_and_b32_e32 v106, 0xffff0000, v228
	v_fma_f32 v139, v223, v99, v103
	v_sub_f32_e32 v99, v102, v106
	v_fma_f32 v99, v222, v99, v106
	v_mul_f32_e32 v128, v99, v125
	v_mul_f32_e32 v102, v128, v128
	v_or_b32_e32 v140, 1, v212
	v_mad_u64_u32 v[104:105], s[14:15], v140, s97, v[192:193]
	v_mov_b32_dpp v102, v102 quad_perm:[1,0,3,2] row_mask:0xf bank_mask:0xf
	v_fmac_f32_e32 v102, v128, v128
	v_lshl_add_u32 v120, v104, 2, 0
	ds_read2st64_b32 v[104:105], v120 offset1:68
	s_nop 1
	v_add_f32_dpp v102, v102, v102 quad_perm:[2,3,0,1] row_mask:0xf bank_mask:0xf
	s_nop 1
	v_add_f32_dpp v102, v102, v102 row_half_mirror row_mask:0xf bank_mask:0xf
	s_nop 1
	v_add_f32_dpp v102, v102, v102 row_mirror row_mask:0xf bank_mask:0xf
	s_nop 0
	v_readlane_b32 s49, v102, 0
	v_readlane_b32 s74, v102, 16
	v_readlane_b32 s73, v102, 32
	v_readlane_b32 s75, v102, 48
	s_waitcnt lgkmcnt(0)
	v_add_f32_e32 v102, -1.0, v105
	v_fma_f32 v102, v117, v102, 1.0
	v_mul_f32_e32 v99, v99, v102
	v_mul_f32_e32 v102, v139, v99
	v_mul_f32_e32 v107, v124, v102
	s_nop 1
	v_mov_b32_dpp v107, v107 quad_perm:[1,0,3,2] row_mask:0xf bank_mask:0xf
	v_fmac_f32_e32 v107, v124, v102
	s_nop 1
	v_add_f32_dpp v102, v107, v107 quad_perm:[2,3,0,1] row_mask:0xf bank_mask:0xf
	s_nop 1
	v_add_f32_dpp v102, v102, v102 row_half_mirror row_mask:0xf bank_mask:0xf
	s_nop 1
	v_add_f32_dpp v102, v102, v102 row_mirror row_mask:0xf bank_mask:0xf
	s_nop 1
	v_add_f32_dpp v102, v102, v102 row_bcast:15 row_mask:0xa bank_mask:0xf
	s_nop 1
	v_add_f32_dpp v102, v102, v102 row_bcast:31 row_mask:0xc bank_mask:0xf
	s_nop 0
	v_readlane_b32 s44, v102, 63
	s_nop 1
	v_writelane_b32 v200, s44, 1
	v_and_b32_e32 v108, 0xffff0000, v227
	v_sub_f32_e32 v102, v103, v108
	v_lshlrev_b32_e32 v103, 16, v226
	v_fma_f32 v141, v223, v102, v108
	v_sub_f32_e32 v102, v106, v103
	v_fma_f32 v102, v222, v102, v103
	v_mul_f32_e32 v129, v102, v125
	v_mul_f32_e32 v109, v129, v129
	v_add_u32_e32 v106, 16, v120
	ds_read2st64_b32 v[106:107], v106 offset0:1 offset1:69
	v_mov_b32_dpp v109, v109 quad_perm:[1,0,3,2] row_mask:0xf bank_mask:0xf
	v_fmac_f32_e32 v109, v129, v129
	s_nop 1
	v_add_f32_dpp v109, v109, v109 quad_perm:[2,3,0,1] row_mask:0xf bank_mask:0xf
	s_nop 1
	v_add_f32_dpp v109, v109, v109 row_half_mirror row_mask:0xf bank_mask:0xf
	s_nop 1
	v_add_f32_dpp v109, v109, v109 row_mirror row_mask:0xf bank_mask:0xf
	s_nop 0
	v_readlane_b32 s76, v109, 0
	v_readlane_b32 s78, v109, 16
	v_readlane_b32 s77, v109, 32
	v_readlane_b32 s79, v109, 48
	s_waitcnt lgkmcnt(0)
	v_add_f32_e32 v109, -1.0, v107
	v_fma_f32 v109, v117, v109, 1.0
	v_mul_f32_e32 v102, v102, v109
	v_mul_f32_e32 v109, v141, v102
	v_mul_f32_e32 v110, v124, v109
	s_nop 1
	v_mov_b32_dpp v110, v110 quad_perm:[1,0,3,2] row_mask:0xf bank_mask:0xf
	v_fmac_f32_e32 v110, v124, v109
	s_nop 1
	v_add_f32_dpp v109, v110, v110 quad_perm:[2,3,0,1] row_mask:0xf bank_mask:0xf
	s_nop 1
	v_add_f32_dpp v109, v109, v109 row_half_mirror row_mask:0xf bank_mask:0xf
	s_nop 1
	v_add_f32_dpp v109, v109, v109 row_mirror row_mask:0xf bank_mask:0xf
	s_nop 1
	v_add_f32_dpp v109, v109, v109 row_bcast:15 row_mask:0xa bank_mask:0xf
	s_nop 1
	v_add_f32_dpp v109, v109, v109 row_bcast:31 row_mask:0xc bank_mask:0xf
	s_nop 0
	v_readlane_b32 s44, v109, 63
	s_nop 1
	v_writelane_b32 v200, s44, 2
	v_and_b32_e32 v111, 0xffff0000, v226
	v_sub_f32_e32 v103, v103, v111
	v_fma_f32 v103, v222, v103, v111
	v_mul_f32_e32 v130, v103, v125
	v_mul_f32_e32 v112, v130, v130
	v_lshlrev_b32_e32 v110, 16, v225
	v_sub_f32_e32 v108, v108, v110
	v_mov_b32_dpp v112, v112 quad_perm:[1,0,3,2] row_mask:0xf bank_mask:0xf
	v_fmac_f32_e32 v112, v130, v130
	v_fma_f32 v142, v223, v108, v110
	v_add_u32_e32 v108, 32, v120
	s_nop 1
	v_add_f32_dpp v112, v112, v112 quad_perm:[2,3,0,1] row_mask:0xf bank_mask:0xf
	ds_read2st64_b32 v[108:109], v108 offset0:2 offset1:70
	s_nop 0
	s_nop 1
	v_add_f32_dpp v112, v112, v112 row_half_mirror row_mask:0xf bank_mask:0xf
	s_nop 1
	v_add_f32_dpp v112, v112, v112 row_mirror row_mask:0xf bank_mask:0xf
	s_nop 0
	v_readlane_b32 s80, v112, 0
	v_readlane_b32 s14, v112, 16
	v_readlane_b32 s81, v112, 32
	v_readlane_b32 s15, v112, 48
	s_waitcnt lgkmcnt(0)
; __device__ __forceinline__ float wave_sum(float v) {
;     v += dpp_f(v, 0); v += dpp_f(v, 1); v += dpp_f(v, 2); v += dpp_f(v, 3);
;     const int vi = __float_as_int(v);
;     const float s0 = __int_as_float(__builtin_amdgcn_readlane(vi, 0)), s1 = __int_as_float(__builtin_amdgcn_readlane(vi, 16)), s2 = __int_as_float(__builtin_amdgcn_readlane(vi, 32)), s3 = __int_as_float(__builtin_amdgcn_readlane(vi, 48));
;     return (s0 + s1) + (s2 + s3);
; __device__ __forceinline__ void rwkv_phase_a(const Ctx& C) {
;     ...
;             for (int u = 0; u < 8; ++u) {
;                 const int t = tg8 * 8 + u;
;                 ld[u] = FM(0)[t * MS + ci]; av[u] = FM(1)[t * MS + ci];
;                 const float kr = kx[u] * kkc; const float n2 = wave_sum(kr * kr);
;                 kkv[u] = kr * __builtin_amdgcn_rsqf(fmaxf(n2, 1e-24f));
;                 k2[u] = kx[u] * (1.0f + (av[u] - 1.0f) * kac);
;                 const float bs = wave_sum(rr[u] * k2[u] * rkc);
;                 if (lane == 0) bon[(size_t)(tok0 + t) * 8 + h] = bs;
;                 run += ld[u]; cl[u] = run;
;             }
	v_add_f32_e32 v112, -1.0, v109
	v_fma_f32 v112, v117, v112, 1.0
	v_mul_f32_e32 v103, v103, v112
	v_mul_f32_e32 v112, v142, v103
	v_mul_f32_e32 v113, v124, v112
	s_nop 1
	v_mov_b32_dpp v113, v113 quad_perm:[1,0,3,2] row_mask:0xf bank_mask:0xf
	v_fmac_f32_e32 v113, v124, v112
	s_nop 1
	v_add_f32_dpp v112, v113, v113 quad_perm:[2,3,0,1] row_mask:0xf bank_mask:0xf
	s_nop 1
	v_add_f32_dpp v112, v112, v112 row_half_mirror row_mask:0xf bank_mask:0xf
	s_nop 1
	v_add_f32_dpp v112, v112, v112 row_mirror row_mask:0xf bank_mask:0xf
	s_nop 1
	v_add_f32_dpp v112, v112, v112 row_bcast:15 row_mask:0xa bank_mask:0xf
	s_nop 1
	v_add_f32_dpp v112, v112, v112 row_bcast:31 row_mask:0xc bank_mask:0xf
	s_nop 0
	v_readlane_b32 s44, v112, 63
	s_nop 1
	v_writelane_b32 v200, s44, 3
	v_and_b32_e32 v114, 0xffff0000, v225
	v_sub_f32_e32 v110, v110, v114
	v_lshlrev_b32_e32 v115, 16, v224
	v_fma_f32 v143, v223, v110, v114
	v_sub_f32_e32 v110, v111, v115
	v_fma_f32 v110, v222, v110, v115
	v_add_u32_e32 v111, 48, v120
	v_mul_f32_e32 v131, v110, v125
	ds_read2st64_b32 v[112:113], v111 offset0:3 offset1:71
	v_mul_f32_e32 v111, v131, v131
	s_nop 1
	v_mov_b32_dpp v111, v111 quad_perm:[1,0,3,2] row_mask:0xf bank_mask:0xf
	v_fmac_f32_e32 v111, v131, v131
	s_nop 1
	v_add_f32_dpp v111, v111, v111 quad_perm:[2,3,0,1] row_mask:0xf bank_mask:0xf
	s_nop 1
	v_add_f32_dpp v111, v111, v111 row_half_mirror row_mask:0xf bank_mask:0xf
	s_nop 1
	v_add_f32_dpp v111, v111, v111 row_mirror row_mask:0xf bank_mask:0xf
	s_nop 0
	v_readlane_b32 s88, v111, 0
	v_readlane_b32 s42, v111, 16
	v_readlane_b32 s89, v111, 32
	v_readlane_b32 s43, v111, 48
	s_waitcnt lgkmcnt(0)
	v_add_f32_e32 v111, -1.0, v113
	v_fma_f32 v111, v117, v111, 1.0
	v_mul_f32_e32 v110, v110, v111
	v_mul_f32_e32 v111, v143, v110
	v_mul_f32_e32 v116, v124, v111
	s_nop 1
	v_mov_b32_dpp v116, v116 quad_perm:[1,0,3,2] row_mask:0xf bank_mask:0xf
	v_fmac_f32_e32 v116, v124, v111
	s_nop 1
	v_add_f32_dpp v111, v116, v116 quad_perm:[2,3,0,1] row_mask:0xf bank_mask:0xf
	s_nop 1
	v_add_f32_dpp v111, v111, v111 row_half_mirror row_mask:0xf bank_mask:0xf
	s_nop 1
	v_add_f32_dpp v111, v111, v111 row_mirror row_mask:0xf bank_mask:0xf
	s_nop 1
	v_add_f32_dpp v111, v111, v111 row_bcast:15 row_mask:0xa bank_mask:0xf
	s_nop 1
	v_add_f32_dpp v111, v111, v111 row_bcast:31 row_mask:0xc bank_mask:0xf
	s_nop 0
	v_readlane_b32 s44, v111, 63
	s_nop 1
	v_writelane_b32 v200, s44, 4
	v_lshlrev_b32_e32 v116, 16, v221
	v_sub_f32_e32 v111, v114, v116
	v_and_b32_e32 v118, 0xffff0000, v224
	v_fma_f32 v144, v223, v111, v116
	v_sub_f32_e32 v111, v115, v118
	v_fma_f32 v111, v222, v111, v118
	v_mul_f32_e32 v132, v111, v125
	v_mul_f32_e32 v119, v132, v132
	v_add_u32_e32 v114, 64, v120
	ds_read2st64_b32 v[114:115], v114 offset0:4 offset1:72
	v_mov_b32_dpp v119, v119 quad_perm:[1,0,3,2] row_mask:0xf bank_mask:0xf
	v_fmac_f32_e32 v119, v132, v132
	s_nop 1
	v_add_f32_dpp v119, v119, v119 quad_perm:[2,3,0,1] row_mask:0xf bank_mask:0xf
	s_nop 1
	v_add_f32_dpp v119, v119, v119 row_half_mirror row_mask:0xf bank_mask:0xf
	s_nop 1
	v_add_f32_dpp v119, v119, v119 row_mirror row_mask:0xf bank_mask:0xf
	s_nop 0
	v_readlane_b32 s90, v119, 0
	v_readlane_b32 s60, v119, 16
	v_readlane_b32 s70, v119, 32
	v_readlane_b32 s52, v119, 48
	s_waitcnt lgkmcnt(0)
	v_add_f32_e32 v119, -1.0, v115
	v_fma_f32 v119, v117, v119, 1.0
	v_mul_f32_e32 v111, v111, v119
	v_mul_f32_e32 v119, v144, v111
	v_mul_f32_e32 v121, v124, v119
	s_nop 1
	v_mov_b32_dpp v121, v121 quad_perm:[1,0,3,2] row_mask:0xf bank_mask:0xf
	v_fmac_f32_e32 v121, v124, v119
	s_nop 1
	v_add_f32_dpp v119, v121, v121 quad_perm:[2,3,0,1] row_mask:0xf bank_mask:0xf
	s_nop 1
	v_add_f32_dpp v119, v119, v119 row_half_mirror row_mask:0xf bank_mask:0xf
	s_nop 1
	v_add_f32_dpp v119, v119, v119 row_mirror row_mask:0xf bank_mask:0xf
	s_nop 1
	v_add_f32_dpp v119, v119, v119 row_bcast:15 row_mask:0xa bank_mask:0xf
	s_nop 1
	v_add_f32_dpp v119, v119, v119 row_bcast:31 row_mask:0xc bank_mask:0xf
	s_nop 0
	v_readlane_b32 s44, v119, 63
	s_nop 1
	v_writelane_b32 v200, s44, 5
	v_and_b32_e32 v134, 0xffff0000, v221
	v_sub_f32_e32 v116, v116, v134
	v_lshlrev_b32_e32 v121, 16, v220
	v_fma_f32 v145, v223, v116, v134
	v_sub_f32_e32 v116, v118, v121
	v_fma_f32 v116, v222, v116, v121
	v_mul_f32_e32 v133, v116, v125
	v_mul_f32_e32 v135, v133, v133
	v_add_u32_e32 v118, 0x50, v120
	ds_read2st64_b32 v[118:119], v118 offset0:5 offset1:73
	v_mov_b32_dpp v135, v135 quad_perm:[1,0,3,2] row_mask:0xf bank_mask:0xf
	v_fmac_f32_e32 v135, v133, v133
	s_nop 1
	v_add_f32_dpp v135, v135, v135 quad_perm:[2,3,0,1] row_mask:0xf bank_mask:0xf
	s_nop 1
	v_add_f32_dpp v135, v135, v135 row_half_mirror row_mask:0xf bank_mask:0xf
	s_nop 1
	v_add_f32_dpp v135, v135, v135 row_mirror row_mask:0xf bank_mask:0xf
	s_nop 0
	v_readlane_b32 s53, v135, 0
	v_readlane_b32 s55, v135, 16
	v_readlane_b32 s54, v135, 32
	v_readlane_b32 s58, v135, 48
	s_waitcnt lgkmcnt(0)
; __device__ __forceinline__ void rwkv_phase_a(const Ctx& C) {
;     ...
;             for (int u = 0; u < 8; ++u) {
;                 const int t = tg8 * 8 + u;
;                 ld[u] = FM(0)[t * MS + ci]; av[u] = FM(1)[t * MS + ci];
;                 const float kr = kx[u] * kkc; const float n2 = wave_sum(kr * kr);
;                 kkv[u] = kr * __builtin_amdgcn_rsqf(fmaxf(n2, 1e-24f));
;                 k2[u] = kx[u] * (1.0f + (av[u] - 1.0f) * kac);
;                 const float bs = wave_sum(rr[u] * k2[u] * rkc);
;                 if (lane == 0) bon[(size_t)(tok0 + t) * 8 + h] = bs;
;                 run += ld[u]; cl[u] = run;
;             }
;             misc[64 + tg8 * 64 + ci] = run;
;             __syncthreads();
;             float pre = 0.f, tot = 0.f;
; #pragma unroll
;             for (int g = 0; g < 8; ++g) { const float v = misc[64 + g * 64 + ci]; tot += v; if (g < tg8) pre += v; }
;             if (tg8 == 0) misc[ci] = __expf(tot);
	v_add_f32_e32 v135, -1.0, v119
	v_fma_f32 v135, v117, v135, 1.0
	v_mul_f32_e32 v116, v116, v135
	v_mul_f32_e32 v135, v145, v116
	v_mul_f32_e32 v136, v124, v135
	s_nop 1
	v_mov_b32_dpp v136, v136 quad_perm:[1,0,3,2] row_mask:0xf bank_mask:0xf
	v_fmac_f32_e32 v136, v124, v135
	s_nop 1
	v_add_f32_dpp v135, v136, v136 quad_perm:[2,3,0,1] row_mask:0xf bank_mask:0xf
	s_nop 1
	v_add_f32_dpp v135, v135, v135 row_half_mirror row_mask:0xf bank_mask:0xf
	s_nop 1
	v_add_f32_dpp v135, v135, v135 row_mirror row_mask:0xf bank_mask:0xf
	s_nop 1
	v_add_f32_dpp v135, v135, v135 row_bcast:15 row_mask:0xa bank_mask:0xf
	s_nop 1
	v_add_f32_dpp v135, v135, v135 row_bcast:31 row_mask:0xc bank_mask:0xf
	s_nop 0
	v_readlane_b32 s44, v135, 63
	s_nop 1
	v_writelane_b32 v200, s44, 6
	v_lshlrev_b32_e32 v146, 16, v219
	v_sub_f32_e32 v134, v134, v146
	v_fmac_f32_e32 v146, v223, v134
	v_and_b32_e32 v134, 0xffff0000, v220
	v_sub_f32_e32 v121, v121, v134
	v_fmac_f32_e32 v134, v222, v121
	v_mul_f32_e32 v125, v134, v125
	v_mul_f32_e32 v135, v125, v125
	v_add_u32_e32 v120, 0x60, v120
	ds_read2st64_b32 v[120:121], v120 offset0:6 offset1:74
	v_mov_b32_dpp v135, v135 quad_perm:[1,0,3,2] row_mask:0xf bank_mask:0xf
	v_fmac_f32_e32 v135, v125, v125
	s_nop 1
	v_add_f32_dpp v135, v135, v135 quad_perm:[2,3,0,1] row_mask:0xf bank_mask:0xf
	s_nop 1
	v_add_f32_dpp v135, v135, v135 row_half_mirror row_mask:0xf bank_mask:0xf
	s_nop 1
	v_add_f32_dpp v135, v135, v135 row_mirror row_mask:0xf bank_mask:0xf
	s_nop 0
	v_readlane_b32 s59, v135, 0
	v_readlane_b32 s65, v135, 16
	v_readlane_b32 s64, v135, 32
	v_readlane_b32 s66, v135, 48
	s_waitcnt lgkmcnt(0)
	v_add_f32_e32 v135, -1.0, v121
	v_fma_f32 v117, v117, v135, 1.0
	v_mul_f32_e32 v117, v134, v117
	v_mul_f32_e32 v134, v146, v117
	v_mul_f32_e32 v135, v124, v134
	s_nop 1
	v_mov_b32_dpp v135, v135 quad_perm:[1,0,3,2] row_mask:0xf bank_mask:0xf
	v_fmac_f32_e32 v135, v124, v134
	s_nop 1
	v_add_f32_dpp v124, v135, v135 quad_perm:[2,3,0,1] row_mask:0xf bank_mask:0xf
	s_nop 1
	v_add_f32_dpp v124, v124, v124 row_half_mirror row_mask:0xf bank_mask:0xf
	s_nop 1
	v_add_f32_dpp v124, v124, v124 row_mirror row_mask:0xf bank_mask:0xf
	s_nop 1
	v_add_f32_dpp v124, v124, v124 row_bcast:15 row_mask:0xa bank_mask:0xf
	s_nop 1
	v_add_f32_dpp v124, v124, v124 row_bcast:31 row_mask:0xc bank_mask:0xf
	s_nop 0
	v_readlane_b32 s44, v124, 63
	s_nop 1
	v_writelane_b32 v200, s44, 7
	v_add_u32_e32 v198, s31, v212
	v_add_u32_e32 v198, v198, v192
	v_ashrrev_i32_e32 v199, 31, v198
	s_add_u32 s98, s26, s16
	s_addc_u32 s99, s27, s17
	v_lshlrev_b64 v[198:199], 5, v[198:199]
	v_lshl_add_u64 v[198:199], s[98:99], 0, v[198:199]
	s_mov_b64 s[100:101], exec
	s_mov_b64 exec, 0xff
	global_store_dword v[198:199], v200, off
	s_mov_b64 exec, s[100:101]
	v_add_f32_e32 v155, 0, v100
	v_add_f32_e32 v154, v155, v104
	v_add_f32_e32 v153, v154, v106
	v_add_f32_e32 v152, v153, v108
	v_add_f32_e32 v151, v152, v112
	v_add_f32_e32 v150, v151, v114
	v_and_b32_e32 v124, 0x3fffffc0, v210
	v_add_f32_e32 v148, v150, v118
	v_lshlrev_b32_e32 v124, 2, v124
	v_lshlrev_b32_e32 v134, 2, v192
	v_add_f32_e32 v147, v148, v120
	v_add3_u32 v124, s7, v124, v134
	ds_write_b32 v124, v147 offset:256
	v_add_u32_e32 v124, 0, v134
	v_add_u32_e32 v134, 0x25900, v124
	v_add_u32_e32 v135, 0x25a00, v124
	v_add_u32_e32 v136, 0x25b00, v124
	v_add_u32_e32 v149, 0x25c00, v124
	v_add_u32_e32 v156, 0x25d00, v124
	v_add_u32_e32 v160, 0x25e00, v124
	v_add_u32_e32 v161, 0x25f00, v124
	v_add_u32_e32 v124, 0x26000, v124
	s_waitcnt lgkmcnt(0)
	s_barrier
	ds_read_b32 v162, v134
	ds_read_b32 v159, v135
	ds_read_b32 v158, v136
	ds_read_b32 v157, v149
	ds_read_b32 v156, v156
	ds_read_b32 v135, v160
	ds_read_b32 v134, v161
	ds_read_b32 v124, v124
	s_waitcnt lgkmcnt(7)
	v_add_f32_e32 v160, 0, v162
	s_waitcnt lgkmcnt(6)
	v_add_f32_e32 v136, v160, v159
	s_waitcnt lgkmcnt(5)
	v_add_f32_e32 v136, v136, v158
	s_waitcnt lgkmcnt(4)
	v_add_f32_e32 v136, v136, v157
	s_waitcnt lgkmcnt(3)
	v_add_f32_e32 v136, v136, v156
	s_waitcnt lgkmcnt(2)
	v_add_f32_e32 v136, v136, v135
	s_waitcnt lgkmcnt(1)
	v_add_f32_e32 v136, v136, v134
	s_waitcnt lgkmcnt(0)
	v_add_f32_e32 v149, v136, v124
	v_cmp_gt_u32_e32 vcc, 64, v210
	v_lshl_add_u32 v136, v192, 2, 0
	s_and_saveexec_b64 s[22:23], vcc
	s_cbranch_execz .LBB0_739
	v_mul_f32_e32 v161, 0x3fb8aa3b, v149
	v_exp_f32_e32 v161, v161
	v_add_u32_e32 v162, 0x25800, v136
	ds_write_b32 v162, v161
